# GDN scan loop: 41 of the 44 per-step LDS fragment reads renamed to private registers (live-range aware) and issued in batches of up to 12 with counted lgkmcnt waits
# speedup vs baseline: 1.0031x; 1.0002x over previous
.LBB0_1067:
	s_bitcmp1_b32 s13, 0
	s_cselect_b32 s10, 0xe000, 0
	v_add_u32_e32 v170, s10, v168
	v_lshlrev_b32_e32 v80, 16, v68
	v_and_b32_e32 v81, 0xffff0000, v68
	v_lshlrev_b32_e32 v64, 16, v144
	v_and_b32_e32 v65, 0xffff0000, v144
	v_lshlrev_b32_e32 v82, 16, v69
	v_and_b32_e32 v83, 0xffff0000, v69
	v_lshlrev_b32_e32 v66, 16, v145
	v_and_b32_e32 v67, 0xffff0000, v145
	v_lshlrev_b32_e32 v84, 16, v70
	v_and_b32_e32 v85, 0xffff0000, v70
	v_lshlrev_b32_e32 v68, 16, v146
	v_and_b32_e32 v69, 0xffff0000, v146
	v_lshlrev_b32_e32 v86, 16, v71
	v_and_b32_e32 v87, 0xffff0000, v71
	v_lshlrev_b32_e32 v70, 16, v147
	v_and_b32_e32 v71, 0xffff0000, v147
	ds_read_b128 v[176:179], v170
	ds_read_b128 v[180:183], v170 offset:1024
	ds_read_b128 v[184:187], v170 offset:2048
	ds_read_b128 v[188:191], v170 offset:3072
	ds_read_b128 v[192:195], v170 offset:4096
	ds_read_b128 v[196:199], v170 offset:5120
	ds_read_b128 v[200:203], v170 offset:6144
	ds_read_b128 v[214:217], v170 offset:7168
	ds_read_b128 v[218:221], v170 offset:8192
	ds_read_b128 v[222:225], v170 offset:9216
	ds_read_b128 v[226:229], v170 offset:10240
	ds_read_b128 v[230:233], v170 offset:11264
	v_lshlrev_b32_e32 v88, 16, v92
	v_and_b32_e32 v89, 0xffff0000, v92
	v_lshlrev_b32_e32 v90, 16, v93
	v_and_b32_e32 v91, 0xffff0000, v93
	v_lshlrev_b32_e32 v92, 16, v94
	v_and_b32_e32 v93, 0xffff0000, v94
	v_lshlrev_b32_e32 v94, 16, v95
	v_and_b32_e32 v95, 0xffff0000, v95
	v_lshlrev_b32_e32 v72, 16, v76
	v_and_b32_e32 v73, 0xffff0000, v76
	s_waitcnt lgkmcnt(11)
	v_mfma_f32_32x32x16_bf16 v[80:95], v[176:179], v[112:115], v[80:95]
	v_lshlrev_b32_e32 v74, 16, v77
	v_and_b32_e32 v75, 0xffff0000, v77
	v_lshlrev_b32_e32 v76, 16, v78
	v_and_b32_e32 v77, 0xffff0000, v78
	v_lshlrev_b32_e32 v78, 16, v79
	v_and_b32_e32 v79, 0xffff0000, v79
	s_waitcnt lgkmcnt(10)
	v_mfma_f32_32x32x16_bf16 v[80:95], v[180:183], v[116:119], v[80:95]
	v_mul_f32_e64 v14, v14, v164
	v_mul_f32_e64 v15, v15, v164
	v_mul_f32_e64 v12, v12, v164
	v_mul_f32_e64 v13, v13, v164
	v_pk_mul_f32 v[10:11], v[10:11], v[164:165] op_sel_hi:[1,0]
	v_pk_mul_f32 v[8:9], v[8:9], v[164:165] op_sel_hi:[1,0]
	v_pk_mul_f32 v[6:7], v[6:7], v[164:165] op_sel_hi:[1,0]
	v_pk_mul_f32 v[4:5], v[4:5], v[164:165] op_sel_hi:[1,0]
	s_waitcnt lgkmcnt(9)
	v_mfma_f32_32x32x16_bf16 v[80:95], v[184:187], v[120:123], v[80:95]
	v_mul_f32_e64 v2, v2, v164
	v_mul_f32_e64 v3, v3, v164
	v_mul_f32_e64 v0, v0, v164
	v_mul_f32_e64 v1, v1, v164
	v_pk_mul_f32 v[30:31], v[30:31], v[164:165] op_sel_hi:[1,0]
	v_pk_mul_f32 v[28:29], v[28:29], v[164:165] op_sel_hi:[1,0]
	v_pk_mul_f32 v[26:27], v[26:27], v[164:165] op_sel_hi:[1,0]
	v_pk_mul_f32 v[24:25], v[24:25], v[164:165] op_sel_hi:[1,0]
	s_waitcnt lgkmcnt(8)
	v_mfma_f32_32x32x16_bf16 v[80:95], v[188:191], v[124:127], v[80:95]
	v_mul_f32_e64 v22, v22, v164
	v_mul_f32_e64 v23, v23, v164
	v_mul_f32_e64 v20, v20, v164
	v_mul_f32_e64 v21, v21, v164
	v_pk_mul_f32 v[18:19], v[18:19], v[164:165] op_sel_hi:[1,0]
	v_pk_mul_f32 v[16:17], v[16:17], v[164:165] op_sel_hi:[1,0]
	v_pk_mul_f32 v[46:47], v[46:47], v[164:165] op_sel_hi:[1,0]
	v_pk_mul_f32 v[44:45], v[44:45], v[164:165] op_sel_hi:[1,0]
	s_waitcnt lgkmcnt(7)
	v_mfma_f32_32x32x16_bf16 v[80:95], v[192:195], v[128:131], v[80:95]
	v_mul_f32_e64 v42, v42, v164
	v_mul_f32_e64 v43, v43, v164
	v_mul_f32_e64 v40, v40, v164
	v_mul_f32_e64 v41, v41, v164
	v_pk_mul_f32 v[38:39], v[38:39], v[164:165] op_sel_hi:[1,0]
	v_pk_mul_f32 v[36:37], v[36:37], v[164:165] op_sel_hi:[1,0]
	v_pk_mul_f32 v[34:35], v[34:35], v[164:165] op_sel_hi:[1,0]
	v_pk_mul_f32 v[32:33], v[32:33], v[164:165] op_sel_hi:[1,0]
	s_waitcnt lgkmcnt(6)
	v_mfma_f32_32x32x16_bf16 v[80:95], v[196:199], v[132:135], v[80:95]
	v_mul_f32_e64 v62, v62, v164
	v_mul_f32_e64 v63, v63, v164
	v_mul_f32_e64 v60, v60, v164
	v_mul_f32_e64 v61, v61, v164
	v_pk_mul_f32 v[58:59], v[58:59], v[164:165] op_sel_hi:[1,0]
	v_pk_mul_f32 v[56:57], v[56:57], v[164:165] op_sel_hi:[1,0]
	v_pk_mul_f32 v[54:55], v[54:55], v[164:165] op_sel_hi:[1,0]
	v_pk_mul_f32 v[52:53], v[52:53], v[164:165] op_sel_hi:[1,0]
	s_waitcnt lgkmcnt(5)
	v_mfma_f32_32x32x16_bf16 v[80:95], v[200:203], v[136:139], v[80:95]
	v_mul_f32_e64 v50, v50, v164
	v_mul_f32_e64 v51, v51, v164
	v_mul_f32_e64 v48, v48, v164
	v_mul_f32_e64 v49, v49, v164
	s_waitcnt lgkmcnt(4)
	v_mfma_f32_32x32x16_bf16 v[80:95], v[214:217], v[140:143], v[80:95]
	s_waitcnt lgkmcnt(3)
	v_mfma_f32_32x32x16_bf16 v[64:79], v[218:221], v[112:115], v[64:79]
	s_waitcnt lgkmcnt(2)
	v_mfma_f32_32x32x16_bf16 v[64:79], v[222:225], v[116:119], v[64:79]
	s_waitcnt lgkmcnt(1)
	v_mfma_f32_32x32x16_bf16 v[64:79], v[226:229], v[120:123], v[64:79]
	s_waitcnt lgkmcnt(0)
	v_mfma_f32_32x32x16_bf16 v[64:79], v[230:233], v[124:127], v[64:79]
	ds_read_b128 v[176:179], v170 offset:12288
	ds_read_b128 v[180:183], v170 offset:13312
	ds_read_b128 v[184:187], v170 offset:14336
	ds_read_b128 v[188:191], v170 offset:32768
	ds_read_b128 v[192:195], v170 offset:17408
	ds_read_b128 v[196:199], v170 offset:33792
	ds_read_b128 v[200:203], v170 offset:34816
	ds_read_b128 v[214:217], v170 offset:35840
	ds_read_b128 v[218:221], v170 offset:36864
	ds_read_b128 v[222:225], v170 offset:37888
	ds_read_b128 v[226:229], v170 offset:38912
	ds_read_b128 v[230:233], v170 offset:39936
	s_waitcnt lgkmcnt(11)
	v_mfma_f32_32x32x16_bf16 v[64:79], v[176:179], v[128:131], v[64:79]
	s_waitcnt lgkmcnt(10)
	v_mfma_f32_32x32x16_bf16 v[64:79], v[180:183], v[132:135], v[64:79]
	s_waitcnt lgkmcnt(9)
	v_mfma_f32_32x32x16_bf16 v[64:79], v[184:187], v[136:139], v[64:79]
	ds_read_b128 v[144:147], v170 offset:15360
	s_waitcnt lgkmcnt(0)
	v_mfma_f32_32x32x16_bf16 v[64:79], v[144:147], v[140:143], v[64:79]
	v_cvt_pk_bf16_f32 v144, v80, v81
	v_cvt_pk_bf16_f32 v145, v82, v83
	v_cvt_pk_bf16_f32 v146, v84, v85
	v_cvt_pk_bf16_f32 v147, v86, v87
	v_cvt_pk_bf16_f32 v80, v88, v89
	v_cvt_pk_bf16_f32 v81, v90, v91
	v_cvt_pk_bf16_f32 v82, v92, v93
	v_cvt_pk_bf16_f32 v83, v94, v95
	v_cvt_pk_bf16_f32 v88, v64, v65
	v_cvt_pk_bf16_f32 v89, v66, v67
	v_cvt_pk_bf16_f32 v90, v68, v69
	v_cvt_pk_bf16_f32 v91, v70, v71
	v_cvt_pk_bf16_f32 v84, v72, v73
	v_cvt_pk_bf16_f32 v85, v74, v75
	v_cvt_pk_bf16_f32 v86, v76, v77
	v_cvt_pk_bf16_f32 v87, v78, v79
	s_nop 11
	s_waitcnt lgkmcnt(0)
	v_mfma_f32_32x32x16_bf16 v[0:15], v[188:191], v[144:147], v[0:15]
	v_mov_b32_e32 v93, 0
	v_add_u32_e32 v92, s12, v149
	s_waitcnt lgkmcnt(0)
	v_mfma_f32_32x32x16_bf16 v[0:15], v[196:199], v[80:83], v[0:15]
	s_waitcnt lgkmcnt(0)
	v_mfma_f32_32x32x16_bf16 v[0:15], v[200:203], v[88:91], v[0:15]
	s_waitcnt lgkmcnt(0)
	v_mfma_f32_32x32x16_bf16 v[0:15], v[214:217], v[84:87], v[0:15]
	s_waitcnt lgkmcnt(0)
	v_mfma_f32_32x32x16_bf16 v[16:31], v[218:221], v[144:147], v[16:31]
	s_waitcnt lgkmcnt(0)
	v_mfma_f32_32x32x16_bf16 v[16:31], v[222:225], v[80:83], v[16:31]
	s_waitcnt lgkmcnt(0)
	v_mfma_f32_32x32x16_bf16 v[16:31], v[226:229], v[88:91], v[16:31]
	s_waitcnt lgkmcnt(0)
	v_mfma_f32_32x32x16_bf16 v[16:31], v[230:233], v[84:87], v[16:31]
	ds_read_b128 v[176:179], v170 offset:40960
	ds_read_b128 v[180:183], v170 offset:41984
	ds_read_b128 v[184:187], v170 offset:43008
	ds_read_b128 v[188:191], v170 offset:44032
	ds_read_b128 v[196:199], v170 offset:45056
	ds_read_b128 v[200:203], v170 offset:46080
	ds_read_b128 v[214:217], v170 offset:47104
	ds_read_b128 v[218:221], v170 offset:48128
	ds_read_b128 v[222:225], v170 offset:18432
	ds_read_b128 v[226:229], v170 offset:19456
	ds_read_b128 v[230:233], v170 offset:20480
	s_waitcnt lgkmcnt(10)
	v_mfma_f32_32x32x16_bf16 v[32:47], v[176:179], v[144:147], v[32:47]
	s_waitcnt lgkmcnt(9)
	v_mfma_f32_32x32x16_bf16 v[32:47], v[180:183], v[80:83], v[32:47]
	s_waitcnt lgkmcnt(8)
	v_mfma_f32_32x32x16_bf16 v[32:47], v[184:187], v[88:91], v[32:47]
	s_waitcnt lgkmcnt(7)
	v_mfma_f32_32x32x16_bf16 v[32:47], v[188:191], v[84:87], v[32:47]
	s_waitcnt lgkmcnt(6)
	v_mfma_f32_32x32x16_bf16 v[48:63], v[196:199], v[144:147], v[48:63]
	s_waitcnt lgkmcnt(5)
	v_mfma_f32_32x32x16_bf16 v[48:63], v[200:203], v[80:83], v[48:63]
	s_waitcnt lgkmcnt(4)
	v_mfma_f32_32x32x16_bf16 v[48:63], v[214:217], v[88:91], v[48:63]
	s_waitcnt lgkmcnt(3)
	v_mfma_f32_32x32x16_bf16 v[48:63], v[218:221], v[84:87], v[48:63]
	ds_read_b128 v[64:67], v170 offset:16384
	s_waitcnt lgkmcnt(0)
	v_mfma_f32_32x32x16_bf16 v[64:79], v[64:67], v[112:115], 0
	v_mfma_f32_32x32x16_bf16 v[64:79], v[192:195], v[116:119], v[64:79]
	s_waitcnt lgkmcnt(0)
	v_mfma_f32_32x32x16_bf16 v[64:79], v[222:225], v[120:123], v[64:79]
	s_waitcnt lgkmcnt(0)
	v_mfma_f32_32x32x16_bf16 v[64:79], v[226:229], v[124:127], v[64:79]
	s_waitcnt lgkmcnt(0)
	v_mfma_f32_32x32x16_bf16 v[64:79], v[230:233], v[128:131], v[64:79]
	ds_read_b128 v[176:179], v170 offset:21504
	ds_read_b128 v[180:183], v170 offset:22528
	ds_read_b128 v[184:187], v170 offset:23552
	ds_read_b128 v[188:191], v170 offset:49152
	ds_read_b128 v[192:195], v170 offset:50176
	ds_read_b128 v[196:199], v170 offset:51200
	s_waitcnt lgkmcnt(5)
	v_mfma_f32_32x32x16_bf16 v[64:79], v[176:179], v[132:135], v[64:79]
	s_waitcnt lgkmcnt(4)
	v_mfma_f32_32x32x16_bf16 v[64:79], v[180:183], v[136:139], v[64:79]
	s_waitcnt lgkmcnt(3)
	v_mfma_f32_32x32x16_bf16 v[64:79], v[184:187], v[140:143], v[64:79]
	s_waitcnt lgkmcnt(2)
	v_mfma_f32_32x32x16_bf16 v[64:79], v[188:191], v[144:147], v[64:79]
	s_waitcnt lgkmcnt(1)
	v_mfma_f32_32x32x16_bf16 v[64:79], v[192:195], v[80:83], v[64:79]
	s_waitcnt lgkmcnt(0)
	v_mfma_f32_32x32x16_bf16 v[64:79], v[196:199], v[88:91], v[64:79]
	ds_read_b128 v[172:175], v170 offset:52224
	s_waitcnt lgkmcnt(0)
	v_mfma_f32_32x32x16_bf16 v[64:79], v[172:175], v[84:87], v[64:79]
	s_nop 11
	v_mov_b32_dpp v93, v64 quad_perm:[1,0,3,2] row_mask:0xf bank_mask:0xf
	s_and_saveexec_b64 s[10:11], vcc
	s_cbranch_execz .LBB0_1069
	v_bfe_u32 v94, v64, 16, 1
	s_movk_i32 s14, 0x7fff
	v_add3_u32 v64, v64, v94, s14
	v_bfe_u32 v94, v93, 16, 1
	v_lshrrev_b32_e32 v64, 16, v64
	v_add3_u32 v93, v93, v94, s14
	s_mov_b32 s14, 0xffff0000
	v_and_or_b32 v64, v93, s14, v64
	s_movk_i32 s14, 0x600
	v_mad_i64_i32 v[94:95], s[14:15], v92, s14, v[150:151]
	global_store_dword v[94:95], v64, off
